# v16 + branch-GEMM epilogues: gate loads of row-blocks 1..3 hoisted to the epilogue top with recounted vmcnt
# speedup vs baseline: 1.0097x; 1.0021x over previous
.LBB0_702:
	global_load_dwordx4 v[140:143], v[120:121], off
	global_load_dwordx4 v[144:147], v[64:65], off offset:2048
	global_load_dwordx4 v[148:151], v[120:121], off offset:16
	global_load_dwordx4 v[190:193], v[64:65], off offset:2064
	s_nop 0
	global_load_dwordx4 v[64:67], v[118:119], off offset:16
	global_load_dwordx4 v[68:71], v[118:119], off
	global_load_dwordx4 v[208:211], v[126:127], off offset:2048
	global_load_dwordx4 v[212:215], v[126:127], off offset:2064
	global_load_dwordx4 v[216:219], v[124:125], off offset:2048
	global_load_dwordx4 v[220:223], v[124:125], off offset:2064
	global_load_dwordx4 v[224:227], v[122:123], off offset:2048
	global_load_dwordx4 v[228:231], v[122:123], off offset:2064
	s_add_i32 s33, s33, s59
	s_add_i32 s40, s40, s41
	s_add_i32 s42, s42, s43
	s_cmpk_lt_i32 s33, 0x100
	s_waitcnt vmcnt(11)
	v_lshlrev_b32_e32 v152, 16, v140
	s_waitcnt vmcnt(10)
	v_lshlrev_b32_e32 v194, 16, v144
	v_and_b32_e32 v153, 0xffff0000, v140
	v_and_b32_e32 v195, 0xffff0000, v144
	v_lshlrev_b32_e32 v140, 16, v141
	v_lshlrev_b32_e32 v144, 16, v145
	v_and_b32_e32 v141, 0xffff0000, v141
	v_and_b32_e32 v145, 0xffff0000, v145
	v_lshlrev_b32_e32 v196, 16, v142
	v_lshlrev_b32_e32 v198, 16, v146
	v_and_b32_e32 v197, 0xffff0000, v142
	v_and_b32_e32 v199, 0xffff0000, v146
	v_lshlrev_b32_e32 v142, 16, v143
	v_lshlrev_b32_e32 v146, 16, v147
	v_and_b32_e32 v143, 0xffff0000, v143
	v_and_b32_e32 v147, 0xffff0000, v147
	s_waitcnt vmcnt(9)
	v_lshlrev_b32_e32 v200, 16, v148
	s_waitcnt vmcnt(8)
	v_lshlrev_b32_e32 v202, 16, v190
	v_and_b32_e32 v201, 0xffff0000, v148
	v_and_b32_e32 v203, 0xffff0000, v190
	v_lshlrev_b32_e32 v148, 16, v149
	v_lshlrev_b32_e32 v190, 16, v191
	v_and_b32_e32 v149, 0xffff0000, v149
	v_and_b32_e32 v191, 0xffff0000, v191
	v_lshlrev_b32_e32 v204, 16, v150
	v_lshlrev_b32_e32 v206, 16, v192
	v_and_b32_e32 v205, 0xffff0000, v150
	v_and_b32_e32 v207, 0xffff0000, v192
	v_lshlrev_b32_e32 v150, 16, v151
	v_lshlrev_b32_e32 v192, 16, v193
	v_and_b32_e32 v151, 0xffff0000, v151
	v_and_b32_e32 v193, 0xffff0000, v193
	v_pk_fma_f32 v[60:61], v[60:61], v[194:195], v[152:153]
	v_pk_fma_f32 v[62:63], v[62:63], v[144:145], v[140:141]
	v_pk_fma_f32 v[56:57], v[56:57], v[198:199], v[196:197]
	v_pk_fma_f32 v[58:59], v[58:59], v[146:147], v[142:143]
	v_pk_fma_f32 v[52:53], v[52:53], v[202:203], v[200:201]
	v_pk_fma_f32 v[54:55], v[54:55], v[190:191], v[148:149]
	v_pk_fma_f32 v[140:141], v[48:49], v[206:207], v[204:205]
	v_pk_fma_f32 v[142:143], v[50:51], v[192:193], v[150:151]
	v_cvt_pk_bf16_f32 v48, v60, v61
	v_cvt_pk_bf16_f32 v49, v62, v63
	v_cvt_pk_bf16_f32 v50, v56, v57
	v_cvt_pk_bf16_f32 v51, v58, v59
	v_cvt_pk_bf16_f32 v52, v52, v53
	v_cvt_pk_bf16_f32 v53, v54, v55
	v_cvt_pk_bf16_f32 v54, v140, v141
	v_cvt_pk_bf16_f32 v55, v142, v143
	global_store_dwordx4 v[120:121], v[48:51], off
	global_store_dwordx4 v[120:121], v[52:55], off offset:16
	s_nop 0
	global_load_dwordx4 v[48:51], v[116:117], off offset:16
	global_load_dwordx4 v[52:55], v[116:117], off
	s_waitcnt vmcnt(10)
	v_lshlrev_b32_e32 v120, 16, v68
	v_and_b32_e32 v121, 0xffff0000, v68
	v_lshlrev_b32_e32 v68, 16, v69
	v_and_b32_e32 v69, 0xffff0000, v69
	v_lshlrev_b32_e32 v126, 16, v70
	v_and_b32_e32 v127, 0xffff0000, v70
	v_lshlrev_b32_e32 v70, 16, v71
	v_and_b32_e32 v71, 0xffff0000, v71
	v_lshlrev_b32_e32 v140, 16, v64
	v_and_b32_e32 v141, 0xffff0000, v64
	v_lshlrev_b32_e32 v64, 16, v65
	v_and_b32_e32 v65, 0xffff0000, v65
	v_lshlrev_b32_e32 v142, 16, v66
	v_and_b32_e32 v143, 0xffff0000, v66
	v_lshlrev_b32_e32 v66, 16, v67
	v_and_b32_e32 v67, 0xffff0000, v67
	s_waitcnt vmcnt(9)
	v_mov_b32_e32 v60, v208
	v_mov_b32_e32 v61, v209
	v_mov_b32_e32 v62, v210
	v_mov_b32_e32 v63, v211
	v_lshlrev_b32_e32 v144, 16, v60
	v_and_b32_e32 v145, 0xffff0000, v60
	v_lshlrev_b32_e32 v60, 16, v61
	v_and_b32_e32 v61, 0xffff0000, v61
	v_lshlrev_b32_e32 v146, 16, v62
	v_and_b32_e32 v147, 0xffff0000, v62
	v_lshlrev_b32_e32 v62, 16, v63
	v_and_b32_e32 v63, 0xffff0000, v63
	s_waitcnt vmcnt(8)
	v_mov_b32_e32 v56, v212
	v_mov_b32_e32 v57, v213
	v_mov_b32_e32 v58, v214
	v_mov_b32_e32 v59, v215
	v_lshlrev_b32_e32 v148, 16, v56
	v_and_b32_e32 v149, 0xffff0000, v56
	v_lshlrev_b32_e32 v56, 16, v57
	v_and_b32_e32 v57, 0xffff0000, v57
	v_lshlrev_b32_e32 v150, 16, v58
	v_and_b32_e32 v151, 0xffff0000, v58
	v_lshlrev_b32_e32 v58, 16, v59
	v_and_b32_e32 v59, 0xffff0000, v59
	v_pk_fma_f32 v[44:45], v[44:45], v[144:145], v[120:121]
	v_pk_fma_f32 v[46:47], v[46:47], v[60:61], v[68:69]
	v_pk_fma_f32 v[40:41], v[40:41], v[146:147], v[126:127]
	v_pk_fma_f32 v[42:43], v[42:43], v[62:63], v[70:71]
	v_pk_fma_f32 v[36:37], v[36:37], v[148:149], v[140:141]
	v_pk_fma_f32 v[38:39], v[38:39], v[56:57], v[64:65]
	v_pk_fma_f32 v[56:57], v[32:33], v[150:151], v[142:143]
	v_pk_fma_f32 v[58:59], v[34:35], v[58:59], v[66:67]
	v_cvt_pk_bf16_f32 v32, v44, v45
	v_cvt_pk_bf16_f32 v33, v46, v47
	v_cvt_pk_bf16_f32 v34, v40, v41
	v_cvt_pk_bf16_f32 v35, v42, v43
	v_cvt_pk_bf16_f32 v36, v36, v37
	v_cvt_pk_bf16_f32 v37, v38, v39
	v_cvt_pk_bf16_f32 v38, v56, v57
	v_cvt_pk_bf16_f32 v39, v58, v59
	global_store_dwordx4 v[118:119], v[32:35], off
	global_store_dwordx4 v[118:119], v[36:39], off offset:16
	s_nop 0
	global_load_dwordx4 v[32:35], v[114:115], off offset:16
	global_load_dwordx4 v[36:39], v[114:115], off
	s_waitcnt vmcnt(4)
	v_lshlrev_b32_e32 v56, 16, v52
	v_and_b32_e32 v57, 0xffff0000, v52
	v_lshlrev_b32_e32 v52, 16, v53
	v_and_b32_e32 v53, 0xffff0000, v53
	v_lshlrev_b32_e32 v58, 16, v54
	v_and_b32_e32 v59, 0xffff0000, v54
	v_lshlrev_b32_e32 v54, 16, v55
	v_and_b32_e32 v55, 0xffff0000, v55
	v_lshlrev_b32_e32 v60, 16, v48
	v_and_b32_e32 v61, 0xffff0000, v48
	v_lshlrev_b32_e32 v48, 16, v49
	v_and_b32_e32 v49, 0xffff0000, v49
	v_lshlrev_b32_e32 v62, 16, v50
	v_and_b32_e32 v63, 0xffff0000, v50
	v_lshlrev_b32_e32 v50, 16, v51
	v_and_b32_e32 v51, 0xffff0000, v51
	s_waitcnt vmcnt(11)
	v_mov_b32_e32 v44, v216
	v_mov_b32_e32 v45, v217
	v_mov_b32_e32 v46, v218
	v_mov_b32_e32 v47, v219
	v_lshlrev_b32_e32 v64, 16, v44
	v_and_b32_e32 v65, 0xffff0000, v44
	v_lshlrev_b32_e32 v44, 16, v45
	v_and_b32_e32 v45, 0xffff0000, v45
	v_lshlrev_b32_e32 v66, 16, v46
	v_and_b32_e32 v67, 0xffff0000, v46
	v_lshlrev_b32_e32 v46, 16, v47
	v_and_b32_e32 v47, 0xffff0000, v47
	s_waitcnt vmcnt(10)
	v_mov_b32_e32 v40, v220
	v_mov_b32_e32 v41, v221
	v_mov_b32_e32 v42, v222
	v_mov_b32_e32 v43, v223
	v_lshlrev_b32_e32 v68, 16, v40
	v_and_b32_e32 v69, 0xffff0000, v40
	v_lshlrev_b32_e32 v40, 16, v41
	v_and_b32_e32 v41, 0xffff0000, v41
	v_lshlrev_b32_e32 v70, 16, v42
	v_and_b32_e32 v71, 0xffff0000, v42
	v_lshlrev_b32_e32 v42, 16, v43
	v_and_b32_e32 v43, 0xffff0000, v43
	v_pk_fma_f32 v[28:29], v[28:29], v[64:65], v[56:57]
	v_pk_fma_f32 v[30:31], v[30:31], v[44:45], v[52:53]
	v_pk_fma_f32 v[24:25], v[24:25], v[66:67], v[58:59]
	v_pk_fma_f32 v[26:27], v[26:27], v[46:47], v[54:55]
	v_pk_fma_f32 v[20:21], v[20:21], v[68:69], v[60:61]
	v_pk_fma_f32 v[22:23], v[22:23], v[40:41], v[48:49]
	v_pk_fma_f32 v[40:41], v[16:17], v[70:71], v[62:63]
	v_pk_fma_f32 v[42:43], v[18:19], v[42:43], v[50:51]
	v_cvt_pk_bf16_f32 v16, v28, v29
	v_cvt_pk_bf16_f32 v17, v30, v31
	v_cvt_pk_bf16_f32 v18, v24, v25
	v_cvt_pk_bf16_f32 v19, v26, v27
	v_cvt_pk_bf16_f32 v20, v20, v21
	v_cvt_pk_bf16_f32 v21, v22, v23
	v_cvt_pk_bf16_f32 v22, v40, v41
	v_cvt_pk_bf16_f32 v23, v42, v43
	global_store_dwordx4 v[116:117], v[16:19], off
	global_store_dwordx4 v[116:117], v[20:23], off offset:16
	s_nop 0
	s_waitcnt vmcnt(2)
	v_lshlrev_b32_e32 v24, 16, v36
	v_and_b32_e32 v25, 0xffff0000, v36
	v_lshlrev_b32_e32 v26, 16, v37
	v_and_b32_e32 v27, 0xffff0000, v37
	v_lshlrev_b32_e32 v28, 16, v38
	v_and_b32_e32 v29, 0xffff0000, v38
	v_lshlrev_b32_e32 v30, 16, v39
	v_and_b32_e32 v31, 0xffff0000, v39
	v_lshlrev_b32_e32 v36, 16, v32
	v_and_b32_e32 v37, 0xffff0000, v32
	v_lshlrev_b32_e32 v32, 16, v33
	v_and_b32_e32 v33, 0xffff0000, v33
	v_lshlrev_b32_e32 v38, 16, v34
	v_and_b32_e32 v39, 0xffff0000, v34
	v_lshlrev_b32_e32 v34, 16, v35
	v_and_b32_e32 v35, 0xffff0000, v35
	s_waitcnt vmcnt(11)
	v_mov_b32_e32 v20, v224
	v_mov_b32_e32 v21, v225
	v_mov_b32_e32 v22, v226
	v_mov_b32_e32 v23, v227
	v_lshlrev_b32_e32 v40, 16, v20
	v_and_b32_e32 v41, 0xffff0000, v20
	v_lshlrev_b32_e32 v20, 16, v21
	v_and_b32_e32 v21, 0xffff0000, v21
	v_lshlrev_b32_e32 v42, 16, v22
	v_and_b32_e32 v43, 0xffff0000, v22
	v_lshlrev_b32_e32 v22, 16, v23
	v_and_b32_e32 v23, 0xffff0000, v23
	s_waitcnt vmcnt(10)
	v_mov_b32_e32 v16, v228
	v_mov_b32_e32 v17, v229
	v_mov_b32_e32 v18, v230
	v_mov_b32_e32 v19, v231
	v_lshlrev_b32_e32 v44, 16, v16
	v_and_b32_e32 v45, 0xffff0000, v16
	v_lshlrev_b32_e32 v16, 16, v17
	v_and_b32_e32 v17, 0xffff0000, v17
	v_lshlrev_b32_e32 v46, 16, v18
	v_and_b32_e32 v47, 0xffff0000, v18
	v_lshlrev_b32_e32 v18, 16, v19
	v_and_b32_e32 v19, 0xffff0000, v19
	v_pk_fma_f32 v[4:5], v[4:5], v[40:41], v[24:25]
	v_pk_fma_f32 v[6:7], v[6:7], v[20:21], v[26:27]
	v_pk_fma_f32 v[20:21], v[0:1], v[42:43], v[28:29]
	v_pk_fma_f32 v[22:23], v[2:3], v[22:23], v[30:31]
	v_pk_fma_f32 v[12:13], v[12:13], v[44:45], v[36:37]
	v_pk_fma_f32 v[14:15], v[14:15], v[16:17], v[32:33]
	v_pk_fma_f32 v[8:9], v[8:9], v[46:47], v[38:39]
	v_pk_fma_f32 v[10:11], v[10:11], v[18:19], v[34:35]
	v_cvt_pk_bf16_f32 v0, v4, v5
	v_cvt_pk_bf16_f32 v1, v6, v7
	v_cvt_pk_bf16_f32 v2, v20, v21
	v_cvt_pk_bf16_f32 v3, v22, v23
	v_cvt_pk_bf16_f32 v4, v12, v13
	v_cvt_pk_bf16_f32 v5, v14, v15
	v_cvt_pk_bf16_f32 v6, v8, v9
	v_cvt_pk_bf16_f32 v7, v10, v11
	global_store_dwordx4 v[114:115], v[0:3], off
	global_store_dwordx4 v[114:115], v[4:7], off offset:16
	s_cbranch_scc0 .LBB0_711

.LBB0_707:
	v_add_u32_e32 v68, s30, v162
	v_or_b32_e32 v64, s34, v165
	v_ashrrev_i32_e32 v69, 31, v68
	v_readlane_b32 s44, v247, 2
	v_ashrrev_i32_e32 v65, 31, v64
	v_lshlrev_b64 v[66:67], 12, v[68:69]
	v_readlane_b32 s48, v247, 6
	v_readlane_b32 s49, v247, 7
	s_lshl_b64 s[30:31], s[30:31], 9
	v_readlane_b32 s76, v247, 61
	v_lshl_add_u64 v[70:71], s[48:49], 0, v[66:67]
	v_lshlrev_b64 v[66:67], 1, v[64:65]
	v_lshl_add_u64 v[64:65], v[70:71], 0, v[66:67]
	global_load_dwordx4 v[114:117], v[64:65], off offset:16
	global_load_dwordx4 v[118:121], v[64:65], off
	v_or_b32_e32 v222, 16, v68
	v_ashrrev_i32_e32 v223, 31, v222
	v_lshlrev_b64 v[224:225], 12, v[222:223]
	v_lshl_add_u64 v[224:225], s[48:49], 0, v[224:225]
	v_lshl_add_u64 v[216:217], v[224:225], 0, v[66:67]
	v_or_b32_e32 v222, 32, v68
	v_ashrrev_i32_e32 v223, 31, v222
	v_lshlrev_b64 v[224:225], 12, v[222:223]
	v_lshl_add_u64 v[224:225], s[48:49], 0, v[224:225]
	v_lshl_add_u64 v[218:219], v[224:225], 0, v[66:67]
	v_or_b32_e32 v222, 48, v68
	v_ashrrev_i32_e32 v223, 31, v222
	v_lshlrev_b64 v[224:225], 12, v[222:223]
	v_lshl_add_u64 v[224:225], s[48:49], 0, v[224:225]
	v_lshl_add_u64 v[220:221], v[224:225], 0, v[66:67]
	global_load_dwordx4 v[192:195], v[216:217], off offset:16
	global_load_dwordx4 v[196:199], v[216:217], off
	global_load_dwordx4 v[200:203], v[218:219], off offset:16
	global_load_dwordx4 v[204:207], v[218:219], off
	global_load_dwordx4 v[208:211], v[220:221], off offset:16
	global_load_dwordx4 v[212:215], v[220:221], off
	v_readlane_b32 s50, v247, 8
	v_readlane_b32 s51, v247, 9
	s_add_u32 s36, s72, s30
	v_readlane_b32 s90, v248, 11
	v_readlane_b32 s91, v248, 12
	s_addc_u32 s37, s73, s31
	s_lshl_b64 s[30:31], s[34:35], 9
	s_mov_b64 s[50:51], s[90:91]
	s_add_u32 s30, s50, s30
	s_addc_u32 s31, s51, s31
	v_readfirstlane_b32 s24, v169
	s_mov_b32 m0, s24
	v_readfirstlane_b32 s24, v170
	s_mov_b64 s[34:35], 0x1000
	v_readlane_b32 s45, v247, 3
	v_readlane_b32 s46, v247, 4
	v_readlane_b32 s47, v247, 5
	v_readlane_b32 s77, v247, 62
	v_readlane_b32 s78, v247, 63
	v_readlane_b32 s79, v248, 0
	v_readlane_b32 s80, v248, 1
	v_readlane_b32 s81, v248, 2
	v_readlane_b32 s82, v248, 3
	v_readlane_b32 s83, v248, 4
	v_readlane_b32 s84, v248, 5
	v_readlane_b32 s85, v248, 6
	v_readlane_b32 s86, v248, 7
	v_readlane_b32 s87, v248, 8
	v_readlane_b32 s88, v248, 9
	v_readlane_b32 s89, v248, 10
	s_waitcnt vmcnt(6)
	v_lshlrev_b32_e32 v70, 16, v118
	v_and_b32_e32 v71, 0xffff0000, v118
	v_pk_mul_f32 v[60:61], v[60:61], v[70:71]
	v_lshlrev_b32_e32 v70, 16, v119
	v_and_b32_e32 v71, 0xffff0000, v119
	v_pk_mul_f32 v[62:63], v[62:63], v[70:71]
	v_lshlrev_b32_e32 v70, 16, v120
	v_and_b32_e32 v71, 0xffff0000, v120
	v_pk_mul_f32 v[56:57], v[56:57], v[70:71]
	v_lshlrev_b32_e32 v70, 16, v121
	v_and_b32_e32 v71, 0xffff0000, v121
	v_pk_mul_f32 v[58:59], v[58:59], v[70:71]
	v_lshlrev_b32_e32 v70, 16, v114
	v_and_b32_e32 v71, 0xffff0000, v114
	v_pk_mul_f32 v[52:53], v[52:53], v[70:71]
	v_lshlrev_b32_e32 v70, 16, v115
	v_and_b32_e32 v71, 0xffff0000, v115
	v_pk_mul_f32 v[54:55], v[54:55], v[70:71]
	v_lshlrev_b32_e32 v70, 16, v116
	v_and_b32_e32 v71, 0xffff0000, v116
	v_pk_mul_f32 v[70:71], v[48:49], v[70:71]
	v_lshlrev_b32_e32 v48, 16, v117
	v_and_b32_e32 v49, 0xffff0000, v117
	v_pk_mul_f32 v[114:115], v[50:51], v[48:49]
	v_lshlrev_b64 v[48:49], 11, v[68:69]
	v_lshl_add_u64 v[48:49], s[70:71], 0, v[48:49]
	v_cvt_pk_bf16_f32 v50, v56, v57
	v_or_b32_e32 v56, 16, v68
	v_lshl_add_u64 v[120:121], v[48:49], 0, v[66:67]
	v_cvt_pk_bf16_f32 v48, v60, v61
	v_cvt_pk_bf16_f32 v49, v62, v63
	v_cvt_pk_bf16_f32 v51, v58, v59
	v_ashrrev_i32_e32 v57, 31, v56
	v_cvt_pk_bf16_f32 v52, v52, v53
	v_cvt_pk_bf16_f32 v53, v54, v55
	v_cvt_pk_bf16_f32 v54, v70, v71
	v_cvt_pk_bf16_f32 v55, v114, v115
	global_store_dwordx4 v[120:121], v[48:51], off
	global_store_dwordx4 v[120:121], v[52:55], off offset:16
	s_nop 0
	v_lshlrev_b64 v[48:49], 12, v[56:57]
	v_lshl_add_u64 v[48:49], s[48:49], 0, v[48:49]
	v_lshl_add_u64 v[126:127], v[48:49], 0, v[66:67]
	s_waitcnt vmcnt(6)
	v_mov_b32_e32 v48, v192
	v_mov_b32_e32 v49, v193
	v_mov_b32_e32 v50, v194
	v_mov_b32_e32 v51, v195
	v_mov_b32_e32 v52, v196
	v_mov_b32_e32 v53, v197
	v_mov_b32_e32 v54, v198
	v_mov_b32_e32 v55, v199
	v_lshlrev_b32_e32 v58, 16, v52
	v_and_b32_e32 v59, 0xffff0000, v52
	v_lshlrev_b32_e32 v52, 16, v53
	v_and_b32_e32 v53, 0xffff0000, v53
	v_pk_mul_f32 v[46:47], v[46:47], v[52:53]
	v_lshlrev_b32_e32 v52, 16, v54
	v_and_b32_e32 v53, 0xffff0000, v54
	v_pk_mul_f32 v[40:41], v[40:41], v[52:53]
	v_lshlrev_b32_e32 v52, 16, v55
	v_and_b32_e32 v53, 0xffff0000, v55
	v_pk_mul_f32 v[42:43], v[42:43], v[52:53]
	v_lshlrev_b32_e32 v52, 16, v48
	v_and_b32_e32 v53, 0xffff0000, v48
	v_lshlrev_b32_e32 v48, 16, v49
	v_and_b32_e32 v49, 0xffff0000, v49
	v_pk_mul_f32 v[38:39], v[38:39], v[48:49]
	v_lshlrev_b32_e32 v48, 16, v50
	v_and_b32_e32 v49, 0xffff0000, v50
	v_pk_mul_f32 v[48:49], v[32:33], v[48:49]
	v_lshlrev_b32_e32 v32, 16, v51
	v_and_b32_e32 v33, 0xffff0000, v51
	v_pk_mul_f32 v[50:51], v[34:35], v[32:33]
	v_lshlrev_b64 v[32:33], 11, v[56:57]
	v_pk_mul_f32 v[44:45], v[44:45], v[58:59]
	v_lshl_add_u64 v[32:33], s[70:71], 0, v[32:33]
	v_cvt_pk_bf16_f32 v34, v40, v41
	v_or_b32_e32 v40, 32, v68
	v_pk_mul_f32 v[36:37], v[36:37], v[52:53]
	v_lshl_add_u64 v[118:119], v[32:33], 0, v[66:67]
	v_cvt_pk_bf16_f32 v32, v44, v45
	v_cvt_pk_bf16_f32 v33, v46, v47
	v_cvt_pk_bf16_f32 v35, v42, v43
	v_ashrrev_i32_e32 v41, 31, v40
	v_cvt_pk_bf16_f32 v36, v36, v37
	v_cvt_pk_bf16_f32 v37, v38, v39
	v_cvt_pk_bf16_f32 v38, v48, v49
	v_cvt_pk_bf16_f32 v39, v50, v51
	global_store_dwordx4 v[118:119], v[32:35], off
	global_store_dwordx4 v[118:119], v[36:39], off offset:16
	s_nop 0
	v_lshlrev_b64 v[32:33], 12, v[40:41]
	v_lshl_add_u64 v[32:33], s[48:49], 0, v[32:33]
	v_lshl_add_u64 v[124:125], v[32:33], 0, v[66:67]
	s_waitcnt vmcnt(6)
	v_mov_b32_e32 v32, v200
	v_mov_b32_e32 v33, v201
	v_mov_b32_e32 v34, v202
	v_mov_b32_e32 v35, v203
	v_mov_b32_e32 v36, v204
	v_mov_b32_e32 v37, v205
	v_mov_b32_e32 v38, v206
	v_mov_b32_e32 v39, v207
	v_lshlrev_b32_e32 v42, 16, v36
	v_and_b32_e32 v43, 0xffff0000, v36
	v_lshlrev_b32_e32 v36, 16, v37
	v_and_b32_e32 v37, 0xffff0000, v37
	v_pk_mul_f32 v[30:31], v[30:31], v[36:37]
	v_lshlrev_b32_e32 v36, 16, v38
	v_and_b32_e32 v37, 0xffff0000, v38
	v_pk_mul_f32 v[24:25], v[24:25], v[36:37]
	v_lshlrev_b32_e32 v36, 16, v39
	v_and_b32_e32 v37, 0xffff0000, v39
	v_pk_mul_f32 v[26:27], v[26:27], v[36:37]
	v_lshlrev_b32_e32 v36, 16, v32
	v_and_b32_e32 v37, 0xffff0000, v32
	v_lshlrev_b32_e32 v32, 16, v33
	v_and_b32_e32 v33, 0xffff0000, v33
	v_pk_mul_f32 v[22:23], v[22:23], v[32:33]
	v_lshlrev_b32_e32 v32, 16, v34
	v_and_b32_e32 v33, 0xffff0000, v34
	v_pk_mul_f32 v[32:33], v[16:17], v[32:33]
	v_lshlrev_b32_e32 v16, 16, v35
	v_and_b32_e32 v17, 0xffff0000, v35
	v_pk_mul_f32 v[34:35], v[18:19], v[16:17]
	v_lshlrev_b64 v[16:17], 11, v[40:41]
	v_pk_mul_f32 v[28:29], v[28:29], v[42:43]
	v_lshl_add_u64 v[16:17], s[70:71], 0, v[16:17]
	v_cvt_pk_bf16_f32 v18, v24, v25
	v_or_b32_e32 v24, 48, v68
	v_pk_mul_f32 v[20:21], v[20:21], v[36:37]
	v_lshl_add_u64 v[116:117], v[16:17], 0, v[66:67]
	v_cvt_pk_bf16_f32 v16, v28, v29
	v_cvt_pk_bf16_f32 v17, v30, v31
	v_cvt_pk_bf16_f32 v19, v26, v27
	v_ashrrev_i32_e32 v25, 31, v24
	v_cvt_pk_bf16_f32 v20, v20, v21
	v_cvt_pk_bf16_f32 v21, v22, v23
	v_cvt_pk_bf16_f32 v22, v32, v33
	v_cvt_pk_bf16_f32 v23, v34, v35
	global_store_dwordx4 v[116:117], v[16:19], off
	global_store_dwordx4 v[116:117], v[20:23], off offset:16
	v_lshl_add_u64 v[68:69], s[30:31], 0, v[98:99]
	v_lshlrev_b64 v[16:17], 12, v[24:25]
	v_lshl_add_u64 v[16:17], s[48:49], 0, v[16:17]
	v_lshl_add_u64 v[122:123], v[16:17], 0, v[66:67]
	s_waitcnt vmcnt(6)
	v_mov_b32_e32 v16, v208
	v_mov_b32_e32 v17, v209
	v_mov_b32_e32 v18, v210
	v_mov_b32_e32 v19, v211
	v_mov_b32_e32 v20, v212
	v_mov_b32_e32 v21, v213
	v_mov_b32_e32 v22, v214
	v_mov_b32_e32 v23, v215
	v_lshlrev_b32_e32 v26, 16, v20
	v_and_b32_e32 v27, 0xffff0000, v20
	v_lshlrev_b32_e32 v20, 16, v21
	v_and_b32_e32 v21, 0xffff0000, v21
	v_pk_mul_f32 v[6:7], v[6:7], v[20:21]
	v_lshlrev_b32_e32 v20, 16, v22
	v_and_b32_e32 v21, 0xffff0000, v22
	v_pk_mul_f32 v[20:21], v[0:1], v[20:21]
	v_lshlrev_b32_e32 v0, 16, v23
	v_and_b32_e32 v1, 0xffff0000, v23
	v_pk_mul_f32 v[22:23], v[2:3], v[0:1]
	v_lshlrev_b32_e32 v0, 16, v16
	v_and_b32_e32 v1, 0xffff0000, v16
	v_pk_mul_f32 v[12:13], v[12:13], v[0:1]
	v_lshlrev_b32_e32 v0, 16, v17
	v_and_b32_e32 v1, 0xffff0000, v17
	v_pk_mul_f32 v[14:15], v[14:15], v[0:1]
	v_lshlrev_b32_e32 v0, 16, v18
	v_and_b32_e32 v1, 0xffff0000, v18
	v_pk_mul_f32 v[8:9], v[8:9], v[0:1]
	v_lshlrev_b32_e32 v0, 16, v19
	v_and_b32_e32 v1, 0xffff0000, v19
	v_pk_mul_f32 v[10:11], v[10:11], v[0:1]
	v_lshlrev_b64 v[0:1], 11, v[24:25]
	v_pk_mul_f32 v[4:5], v[4:5], v[26:27]
	v_lshl_add_u64 v[0:1], s[70:71], 0, v[0:1]
	v_lshl_add_u64 v[114:115], v[0:1], 0, v[66:67]
	v_cvt_pk_bf16_f32 v0, v4, v5
	v_cvt_pk_bf16_f32 v1, v6, v7
	v_cvt_pk_bf16_f32 v2, v20, v21
	v_cvt_pk_bf16_f32 v3, v22, v23
	v_lshl_add_u64 v[66:67], s[36:37], 0, v[96:97]
	v_cvt_pk_bf16_f32 v4, v12, v13
	v_cvt_pk_bf16_f32 v5, v14, v15
	v_cvt_pk_bf16_f32 v6, v8, v9
	v_cvt_pk_bf16_f32 v7, v10, v11
	global_store_dwordx4 v[114:115], v[0:3], off
	global_store_dwordx4 v[114:115], v[4:7], off offset:16
	s_barrier
	global_load_lds_dwordx4 v[66:67], off
	v_lshl_add_u64 v[0:1], v[68:69], 0, v[100:101]
	s_mov_b32 m0, s24
	v_readfirstlane_b32 s24, v171
	global_load_lds_dwordx4 v[0:1], off
	v_lshl_add_u64 v[2:3], v[66:67], 0, s[34:35]
	s_mov_b32 m0, s24
	v_readfirstlane_b32 s24, v177
	global_load_lds_dwordx4 v[2:3], off
	v_lshl_add_u64 v[2:3], v[68:69], 0, v[102:103]
	s_mov_b32 m0, s24
	v_readfirstlane_b32 s24, v178
	global_load_lds_dwordx4 v[2:3], off
	v_lshl_add_u64 v[2:3], v[66:67], 0, s[12:13]
	s_mov_b32 m0, s24
	v_readfirstlane_b32 s24, v179
	global_load_lds_dwordx4 v[2:3], off
	v_lshl_add_u64 v[0:1], v[0:1], 0, s[14:15]
	s_mov_b32 m0, s24
	v_readfirstlane_b32 s24, v180
	global_load_lds_dwordx4 v[0:1], off
	v_lshl_add_u64 v[0:1], v[66:67], 0, s[16:17]
	s_mov_b32 m0, s24
	v_readfirstlane_b32 s24, v181
	global_load_lds_dwordx4 v[0:1], off
	v_lshl_add_u64 v[0:1], v[68:69], 0, v[104:105]
	s_mov_b32 m0, s24
	v_lshl_add_u64 v[2:3], s[30:31], 0, v[102:103]
	global_load_lds_dwordx4 v[0:1], off
	v_lshl_add_u64 v[0:1], s[30:31], 0, v[100:101]
	v_lshl_add_u64 v[0:1], v[0:1], 0, v[98:99]
	v_lshl_add_u64 v[140:141], v[0:1], 0, s[8:9]
	v_lshl_add_u64 v[148:149], v[0:1], 0, s[20:21]
	v_lshl_add_u64 v[0:1], s[30:31], 0, v[104:105]
	v_lshl_add_u64 v[2:3], v[2:3], 0, v[98:99]
	v_lshl_add_u64 v[0:1], v[0:1], 0, v[98:99]
	v_mov_b32_e32 v8, 0
	v_lshl_add_u64 v[70:71], v[66:67], 0, s[8:9]
	v_lshl_add_u64 v[142:143], v[66:67], 0, s[18:19]
	v_lshl_add_u64 v[144:145], v[2:3], 0, s[8:9]
	v_lshl_add_u64 v[146:147], v[66:67], 0, s[10:11]
	v_lshl_add_u64 v[150:151], v[66:67], 0, s[22:23]
	v_lshl_add_u64 v[152:153], v[0:1], 0, s[8:9]
	s_mov_b32 s24, 0
	s_mov_b64 s[30:31], -1
	v_mov_b32_e32 v9, v8
	v_mov_b32_e32 v10, v8
	v_mov_b32_e32 v11, v8
	v_mov_b32_e32 v12, v8
	v_mov_b32_e32 v13, v8
	v_mov_b32_e32 v14, v8
	v_mov_b32_e32 v15, v8
	v_mov_b32_e32 v0, v8
	v_mov_b32_e32 v1, v8
	v_mov_b32_e32 v2, v8
	v_mov_b32_e32 v3, v8
	v_mov_b32_e32 v4, v8
	v_mov_b32_e32 v5, v8
	v_mov_b32_e32 v6, v8
	v_mov_b32_e32 v7, v8
	v_mov_b32_e32 v16, v8
	v_mov_b32_e32 v17, v8
	v_mov_b32_e32 v18, v8
	v_mov_b32_e32 v19, v8
	v_mov_b32_e32 v20, v8
	v_mov_b32_e32 v21, v8
	v_mov_b32_e32 v22, v8
	v_mov_b32_e32 v23, v8
	v_mov_b32_e32 v24, v8
	v_mov_b32_e32 v25, v8
	v_mov_b32_e32 v26, v8
	v_mov_b32_e32 v27, v8
	v_mov_b32_e32 v28, v8
	v_mov_b32_e32 v29, v8
	v_mov_b32_e32 v30, v8
	v_mov_b32_e32 v31, v8
	v_mov_b32_e32 v32, v8
	v_mov_b32_e32 v33, v8
	v_mov_b32_e32 v34, v8
	v_mov_b32_e32 v35, v8
	v_mov_b32_e32 v36, v8
	v_mov_b32_e32 v37, v8
	v_mov_b32_e32 v38, v8
	v_mov_b32_e32 v39, v8
	v_mov_b32_e32 v40, v8
	v_mov_b32_e32 v41, v8
	v_mov_b32_e32 v42, v8
	v_mov_b32_e32 v43, v8
	v_mov_b32_e32 v44, v8
	v_mov_b32_e32 v45, v8
	v_mov_b32_e32 v46, v8
	v_mov_b32_e32 v47, v8
	v_mov_b32_e32 v48, v8
	v_mov_b32_e32 v49, v8
	v_mov_b32_e32 v50, v8
	v_mov_b32_e32 v51, v8
	v_mov_b32_e32 v52, v8
	v_mov_b32_e32 v53, v8
	v_mov_b32_e32 v54, v8
	v_mov_b32_e32 v55, v8
	v_mov_b32_e32 v56, v8
	v_mov_b32_e32 v57, v8
	v_mov_b32_e32 v58, v8
	v_mov_b32_e32 v59, v8
	v_mov_b32_e32 v60, v8
	v_mov_b32_e32 v61, v8
	v_mov_b32_e32 v62, v8
	v_mov_b32_e32 v63, v8
	s_waitcnt vmcnt(0) lgkmcnt(0)
	s_barrier
	s_branch .LBB0_709
